# prep_weights tiles behind the scan: second float4 load of a tile issued right behind the first (was load-wait-write-load-wait-write), counted vmcnt
# baseline (speedup 1.0000x reference)
; DI void transpose_tile(const float* __restrict__ src, int Nsrc, int K, bf16_t* __restrict__ dst, int mode, int k0, int n0, float* tile  ) {
;     const int tid = tid_();
;     const int n4 = (tid & 15) * 4;
;     const int c = colmap(mode, n0 + n4);
; #pragma unroll
;     for (int i = 0; i < 2; ++i) {
;         const int kk = (tid >> 4) + 32 * i;
;         f32x4 v = {0.f, 0.f, 0.f, 0.f};
;         if (c >= 0) v = *(const f32x4*)(src + (size_t)(k0 + kk) * Nsrc + c);
;         tile[kk * 65 + n4] = v[0]; tile[kk * 65 + n4 + 1] = v[1]; tile[kk * 65 + n4 + 2] = v[2]; tile[kk * 65 + n4 + 3] = v[3];
;     }
;     __syncthreads();
; DI void prep_weights(const Params& P, unsigned char* smem, int L, int vb, int nvb, int part  ) {
;     ...
;     for (int idx = vb; idx < E6; idx += nvb) {
;         const bool early = (idx < T_W1) || (idx >= E1 && idx < E1 + T_W2) || (idx >= E2 && idx < E3);
;         if (part != 2 && early != (part == 0)) continue;
;         if (idx < E1) { const int j = L * 2 + idx / T_W1, t = idx % T_W1; const int kt = t / 88, nt = t % 88;
;             transpose_tile(P.ffn_w_in + (size_t)j * D * 2 * DFF, 2 * DFF, D, (bf16_t*)(ws + OFF_W1 + j * SZ_W1), 1, kt * 64, nt * 64, tile); }
;         else if (idx < E2) { const int q = idx - E1; const int j = L * 2 + q / T_W2, t = q % T_W2; const int kt = t / 16, nt = t % 16;
;             transpose_tile(P.ffn_w_out + (size_t)j * DFF * D, D, DFF, (bf16_t*)(ws + OFF_W2 + j * SZ_W2), 0, kt * 64, nt * 64, tile); }
;         else if (idx < E3) { const int t = idx - E2; const int kt = t / 60, nt = t % 60;
;             transpose_tile(P.mix_w_in + (size_t)L * D * 3592, 3592, D, (bf16_t*)(ws + OFF_WIN + L * SZ_WIN), 2, kt * 64, nt * 64, tile); }
;         else if (idx < E4) { const int t = idx - E3; const int kt = t / 16, nt = t % 16;
;             transpose_tile(P.mix_w_out + (size_t)L * D * D, D, D, (bf16_t*)(ws + OFF_WOUT + L * SZ_WSQ), 0, kt * 64, nt * 64, tile); }
;         else if (idx < E5) { const int t = idx - E4; const int kt = t / 16, nt = t % 16;
;             transpose_tile(P.ple_w_gate + (size_t)L * D * D, D, D, (bf16_t*)(ws + OFF_WG + L * SZ_WSQ), 0, kt * 64, nt * 64, tile); }
;         else { const int t = idx - E5; const int kt = t / 16, nt = t % 16;
;             transpose_tile(P.ple_w_proj + (size_t)L * PLE * D, D, PLE, (bf16_t*)(ws + OFF_WP + L * SZ_WP), 0, kt * 64, nt * 64, tile); }
.LBB0_333:
	s_add_i32 s11, s10, 0xffffef80
	s_cmpk_gt_i32 s10, 0x57f
	s_cselect_b64 s[6:7], -1, 0
	s_add_i32 s4, s10, 0xfffff240
	s_cmp_lt_u32 s4, 0xfffffd40
	s_cselect_b64 s[12:13], -1, 0
	s_and_b64 s[6:7], s[6:7], s[12:13]
	s_cmpk_gt_u32 s11, 0x3bf
	s_cselect_b64 s[12:13], -1, 0
	s_and_b64 s[6:7], s[6:7], s[12:13]
	s_andn2_b64 vcc, exec, s[6:7]
	s_cbranch_vccnz .LBB0_332
	s_cmpk_gt_u32 s10, 0xaff
	s_mov_b64 s[6:7], -1
	s_cbranch_scc0 .LBB0_362
	s_cmpk_gt_u32 s10, 0x107f
	s_cbranch_scc0 .LBB0_359
	s_cmpk_gt_u32 s10, 0x143f
	s_cbranch_scc0 .LBB0_346
	s_cmpk_gt_u32 s10, 0x153f
	s_cbranch_scc0 .LBB0_343
	s_and_b32 s12, s9, 0x3c0
	s_cmpk_gt_u32 s10, 0x163f
	s_cbranch_scc0 .LBB0_340
	v_mov_b32_e32 v8, v223
	s_and_b32 s4, s8, 0x7fffffc0
	s_addk_i32 s4, 0xa700
	v_lshlrev_b32_e32 v0, 2, v8
	v_and_b32_e32 v0, 60, v0
	v_ashrrev_i32_e32 v9, 4, v8
	v_or_b32_e32 v1, s12, v0
	v_readlane_b32 s16, v250, 58
	v_add_u32_e32 v6, s4, v9
	v_lshlrev_b32_e32 v176, 2, v1
	v_readlane_b32 s26, v249, 4
	v_readlane_b32 s27, v249, 5
	v_ashrrev_i32_e32 v7, 31, v6
	v_lshlrev_b32_e32 v10, 2, v0
	v_lshl_add_u64 v[4:5], s[26:27], 0, v[176:177]
	v_lshlrev_b64 v[0:1], 12, v[6:7]
	v_lshl_add_u64 v[0:1], v[4:5], 0, v[0:1]
	global_load_dwordx4 v[0:3], v[0:1], off
	v_add_u32_e32 v20, 32, v6
	v_ashrrev_i32_e32 v21, 31, v20
	v_lshlrev_b64 v[20:21], 12, v[20:21]
	v_lshl_add_u64 v[20:21], v[4:5], 0, v[20:21]
	global_load_dwordx4 v[16:19], v[20:21], off
	s_movk_i32 s0, 0x104
	v_mul_lo_u32 v7, v9, s0
	v_add3_u32 v7, 0, v10, v7
	s_and_b32 s6, s10, 12
	s_lshr_b32 s4, s4, 6
	s_add_i32 s4, s4, s6
	s_lshl_b64 s[6:7], s[4:5], 8
	s_and_b32 s4, s9, 0xc0
	s_or_b32 s6, s6, s4
	v_readlane_b32 s17, v250, 59
	v_readlane_b32 s18, v250, 60
	v_readlane_b32 s19, v250, 61
	v_readlane_b32 s20, v250, 62
	v_readlane_b32 s21, v250, 63
	v_readlane_b32 s22, v249, 0
	v_readlane_b32 s23, v249, 1
	v_readlane_b32 s24, v249, 2
	v_readlane_b32 s25, v249, 3
	v_readlane_b32 s28, v249, 6
	v_readlane_b32 s29, v249, 7
	v_readlane_b32 s30, v249, 8
	v_readlane_b32 s31, v249, 9
	s_waitcnt vmcnt(1)
	ds_write2_b32 v7, v0, v1 offset1:1
	ds_write2_b32 v7, v2, v3 offset0:2 offset1:3
	v_add_u32_e32 v4, 0x2080, v7
	s_waitcnt vmcnt(0)
	ds_write2_b32 v4, v16, v17 offset1:1
	v_add_u32_e32 v0, 0x2088, v7
	ds_write2_b32 v0, v18, v19 offset1:1
	v_lshlrev_b32_e32 v0, 3, v8
	v_ashrrev_i32_e32 v4, 3, v8
	v_and_b32_e32 v8, 56, v0
	v_mul_u32_u24_e32 v0, 0x104, v8
	v_lshlrev_b32_e32 v1, 2, v4
	v_add3_u32 v5, 0, v0, v1
	s_waitcnt lgkmcnt(0)
	s_barrier
	ds_read2_b32 v[0:1], v5 offset1:65
	ds_read2_b32 v[2:3], v5 offset0:130 offset1:195
	v_add_u32_e32 v5, 0x400, v5
	ds_read2_b32 v[6:7], v5 offset0:134 offset1:199
	v_lshlrev_b32_e32 v176, 1, v8
	v_and_b32_e32 v245, 64, v176
	v_and_b32_e32 v176, 48, v176
	v_lshl_or_b32 v176, v245, 8, v176
	s_waitcnt lgkmcnt(2)
	v_cvt_pk_bf16_f32 v0, v0, v1
	s_waitcnt lgkmcnt(1)
	v_cvt_pk_bf16_f32 v1, v2, v3
	ds_read2_b32 v[2:3], v5 offset0:4 offset1:69
	v_ashrrev_i32_e32 v5, 31, v4
	v_lshl_add_u64 v[4:5], s[6:7], 0, v[4:5]
	v_readlane_b32 s6, v250, 14
	v_and_b32_e32 v246, 0xff, v4
	v_lshlrev_b32_e32 v246, 6, v246
	v_and_b32_e32 v4, 0xffffff00, v4
	v_lshlrev_b64 v[4:5], 7, v[4:5]
	v_or_b32_e32 v4, v4, v246
	v_readlane_b32 s7, v250, 15
	s_waitcnt lgkmcnt(0)
	v_cvt_pk_bf16_f32 v2, v2, v3
	v_cvt_pk_bf16_f32 v3, v6, v7
	v_lshl_add_u64 v[4:5], s[6:7], 0, v[4:5]
	v_lshl_add_u64 v[4:5], v[4:5], 0, v[176:177]
	global_store_dwordx4 v[4:5], v[0:3], off
	s_barrier
	s_mov_b64 s[6:7], 0
.LBB0_340:
	s_andn2_b64 vcc, exec, s[6:7]
	s_cbranch_vccnz .LBB0_342
	v_mov_b32_e32 v8, v223
	s_and_b32 s4, s8, 0x7fc0
	s_addk_i32 s4, 0xab00
	v_lshlrev_b32_e32 v0, 2, v8
	v_and_b32_e32 v0, 60, v0
	v_ashrrev_i32_e32 v9, 4, v8
	v_or_b32_e32 v1, s12, v0
	v_readlane_b32 s12, v250, 58
	v_add_u32_e32 v6, s4, v9
	v_lshlrev_b32_e32 v176, 2, v1
	v_readlane_b32 s24, v249, 6
	v_readlane_b32 s25, v249, 7
	v_ashrrev_i32_e32 v7, 31, v6
	v_lshlrev_b32_e32 v10, 2, v0
	v_lshl_add_u64 v[4:5], s[24:25], 0, v[176:177]
	v_lshlrev_b64 v[0:1], 12, v[6:7]
	v_lshl_add_u64 v[0:1], v[4:5], 0, v[0:1]
	global_load_dwordx4 v[0:3], v[0:1], off
	v_add_u32_e32 v20, 32, v6
	v_ashrrev_i32_e32 v21, 31, v20
	v_lshlrev_b64 v[20:21], 12, v[20:21]
	v_lshl_add_u64 v[20:21], v[4:5], 0, v[20:21]
	global_load_dwordx4 v[16:19], v[20:21], off
	s_movk_i32 s0, 0x104
	v_mul_lo_u32 v7, v9, s0
	v_add3_u32 v7, 0, v10, v7
	s_and_b32 s6, s8, 48
	s_lshr_b32 s4, s4, 6
	s_add_i32 s4, s4, s6
	s_lshl_b64 s[6:7], s[4:5], 8
	s_and_b32 s4, s9, 0xc0
	s_or_b32 s6, s6, s4
	v_readlane_b32 s13, v250, 59
	v_readlane_b32 s14, v250, 60
	v_readlane_b32 s15, v250, 61
	v_readlane_b32 s16, v250, 62
	v_readlane_b32 s17, v250, 63
	v_readlane_b32 s18, v249, 0
	v_readlane_b32 s19, v249, 1
	v_readlane_b32 s20, v249, 2
	v_readlane_b32 s21, v249, 3
	v_readlane_b32 s22, v249, 4
	v_readlane_b32 s23, v249, 5
	v_readlane_b32 s26, v249, 8
	v_readlane_b32 s27, v249, 9
	s_waitcnt vmcnt(1)
	ds_write2_b32 v7, v0, v1 offset1:1
	ds_write2_b32 v7, v2, v3 offset0:2 offset1:3
	v_add_u32_e32 v4, 0x2080, v7
	s_waitcnt vmcnt(0)
	ds_write2_b32 v4, v16, v17 offset1:1
	v_add_u32_e32 v0, 0x2088, v7
	ds_write2_b32 v0, v18, v19 offset1:1
	v_lshlrev_b32_e32 v0, 3, v8
	v_ashrrev_i32_e32 v4, 3, v8
	v_and_b32_e32 v8, 56, v0
	v_mul_u32_u24_e32 v0, 0x104, v8
	v_lshlrev_b32_e32 v1, 2, v4
	v_add3_u32 v5, 0, v0, v1
	s_waitcnt lgkmcnt(0)
	s_barrier
	ds_read2_b32 v[0:1], v5 offset1:65
	ds_read2_b32 v[2:3], v5 offset0:130 offset1:195
	v_add_u32_e32 v5, 0x400, v5
	ds_read2_b32 v[6:7], v5 offset0:134 offset1:199
	v_lshlrev_b32_e32 v176, 1, v8
	v_and_b32_e32 v245, 64, v176
	v_and_b32_e32 v176, 48, v176
	v_lshl_or_b32 v176, v245, 8, v176
	s_waitcnt lgkmcnt(2)
	v_cvt_pk_bf16_f32 v0, v0, v1
	s_waitcnt lgkmcnt(1)
	v_cvt_pk_bf16_f32 v1, v2, v3
	ds_read2_b32 v[2:3], v5 offset0:4 offset1:69
	v_ashrrev_i32_e32 v5, 31, v4
	v_lshl_add_u64 v[4:5], s[6:7], 0, v[4:5]
	v_readlane_b32 s6, v250, 12
	v_and_b32_e32 v246, 0xff, v4
	v_lshlrev_b32_e32 v246, 6, v246
	v_and_b32_e32 v4, 0xffffff00, v4
	v_lshlrev_b64 v[4:5], 7, v[4:5]
	v_or_b32_e32 v4, v4, v246
	v_readlane_b32 s7, v250, 13
	s_waitcnt lgkmcnt(0)
	v_cvt_pk_bf16_f32 v2, v2, v3
	v_cvt_pk_bf16_f32 v3, v6, v7
	v_lshl_add_u64 v[4:5], s[6:7], 0, v[4:5]
	v_lshl_add_u64 v[4:5], v[4:5], 0, v[176:177]
	global_store_dwordx4 v[4:5], v[0:3], off
	s_barrier

; DI int tid_() { int t = threadIdx.x; asm volatile("" : "+v"(t)); return t; }
; DI void transpose_tile(const float* __restrict__ src, int Nsrc, int K, bf16_t* __restrict__ dst, int mode, int k0, int n0, float* tile  ) {
;     const int tid = tid_();
;     const int n4 = (tid & 15) * 4;
;     const int c = colmap(mode, n0 + n4);
; #pragma unroll
;     for (int i = 0; i < 2; ++i) {
;         const int kk = (tid >> 4) + 32 * i;
;         f32x4 v = {0.f, 0.f, 0.f, 0.f};
;         if (c >= 0) v = *(const f32x4*)(src + (size_t)(k0 + kk) * Nsrc + c);
;         tile[kk * 65 + n4] = v[0]; tile[kk * 65 + n4 + 1] = v[1]; tile[kk * 65 + n4 + 2] = v[2]; tile[kk * 65 + n4 + 3] = v[3];
;     }
;     __syncthreads();
; DI void prep_weights(const Params& P, unsigned char* smem, int L, int vb, int nvb, int part  ) {
;     ...
;         else if (idx < E4) { const int t = idx - E3; const int kt = t / 16, nt = t % 16;
;             transpose_tile(P.mix_w_out + (size_t)L * D * D, D, D, (bf16_t*)(ws + OFF_WOUT + L * SZ_WSQ), 0, kt * 64, nt * 64, tile); }
.LBB0_343:
	s_andn2_b64 vcc, exec, s[6:7]
	s_cbranch_vccnz .LBB0_345
	v_mov_b32_e32 v8, v223
	s_and_b32 s4, s8, 0x7fc0
	s_addk_i32 s4, 0xaf00
	v_lshlrev_b32_e32 v0, 2, v8
	s_and_b32 s6, s9, 0x3c0
	v_and_b32_e32 v0, 60, v0
	v_ashrrev_i32_e32 v9, 4, v8
	v_or_b32_e32 v1, s6, v0
	v_readlane_b32 s12, v250, 58
	v_add_u32_e32 v6, s4, v9
	v_lshlrev_b32_e32 v176, 2, v1
	v_readlane_b32 s20, v249, 2
	v_readlane_b32 s21, v249, 3
	v_ashrrev_i32_e32 v7, 31, v6
	v_lshlrev_b32_e32 v10, 2, v0
	v_lshl_add_u64 v[4:5], s[20:21], 0, v[176:177]
	v_lshlrev_b64 v[0:1], 12, v[6:7]
	v_lshl_add_u64 v[0:1], v[4:5], 0, v[0:1]
	global_load_dwordx4 v[0:3], v[0:1], off
	v_add_u32_e32 v20, 32, v6
	v_ashrrev_i32_e32 v21, 31, v20
	v_lshlrev_b64 v[20:21], 12, v[20:21]
	v_lshl_add_u64 v[20:21], v[4:5], 0, v[20:21]
	global_load_dwordx4 v[16:19], v[20:21], off
	s_movk_i32 s0, 0x104
	v_mul_lo_u32 v7, v9, s0
	v_add3_u32 v7, 0, v10, v7
	s_and_b32 s6, s8, 48
	s_lshr_b32 s4, s4, 6
	s_add_i32 s4, s4, s6
	s_lshl_b64 s[6:7], s[4:5], 8
	s_and_b32 s4, s9, 0xc0
	s_or_b32 s6, s6, s4
	v_readlane_b32 s13, v250, 59
	v_readlane_b32 s14, v250, 60
	v_readlane_b32 s15, v250, 61
	v_readlane_b32 s16, v250, 62
	v_readlane_b32 s17, v250, 63
	v_readlane_b32 s18, v249, 0
	v_readlane_b32 s19, v249, 1
	v_readlane_b32 s22, v249, 4
	v_readlane_b32 s23, v249, 5
	v_readlane_b32 s24, v249, 6
	v_readlane_b32 s25, v249, 7
	v_readlane_b32 s26, v249, 8
	v_readlane_b32 s27, v249, 9
	s_waitcnt vmcnt(1)
	ds_write2_b32 v7, v0, v1 offset1:1
	ds_write2_b32 v7, v2, v3 offset0:2 offset1:3
	v_add_u32_e32 v4, 0x2080, v7
	s_waitcnt vmcnt(0)
	ds_write2_b32 v4, v16, v17 offset1:1
	v_add_u32_e32 v0, 0x2088, v7
	ds_write2_b32 v0, v18, v19 offset1:1
	v_lshlrev_b32_e32 v0, 3, v8
	v_ashrrev_i32_e32 v4, 3, v8
	v_and_b32_e32 v8, 56, v0
	v_mul_u32_u24_e32 v0, 0x104, v8
	v_lshlrev_b32_e32 v1, 2, v4
	v_add3_u32 v5, 0, v0, v1
	s_waitcnt lgkmcnt(0)
	s_barrier
	ds_read2_b32 v[0:1], v5 offset1:65
	ds_read2_b32 v[2:3], v5 offset0:130 offset1:195
	v_add_u32_e32 v5, 0x400, v5
	ds_read2_b32 v[6:7], v5 offset0:134 offset1:199
	v_lshlrev_b32_e32 v176, 1, v8
	v_and_b32_e32 v245, 64, v176
	v_and_b32_e32 v176, 48, v176
	v_lshl_or_b32 v176, v245, 8, v176
	s_waitcnt lgkmcnt(2)
	v_cvt_pk_bf16_f32 v0, v0, v1
	s_waitcnt lgkmcnt(1)
	v_cvt_pk_bf16_f32 v1, v2, v3
	ds_read2_b32 v[2:3], v5 offset0:4 offset1:69
	v_ashrrev_i32_e32 v5, 31, v4
	v_lshl_add_u64 v[4:5], s[6:7], 0, v[4:5]
	v_readlane_b32 s6, v250, 16
	v_and_b32_e32 v246, 0xff, v4
	v_lshlrev_b32_e32 v246, 6, v246
	v_and_b32_e32 v4, 0xffffff00, v4
	v_lshlrev_b64 v[4:5], 7, v[4:5]
	v_or_b32_e32 v4, v4, v246
	v_readlane_b32 s7, v250, 17
	s_waitcnt lgkmcnt(0)
	v_cvt_pk_bf16_f32 v2, v2, v3
	v_cvt_pk_bf16_f32 v3, v6, v7
	v_lshl_add_u64 v[4:5], s[6:7], 0, v[4:5]
	v_lshl_add_u64 v[4:5], v[4:5], 0, v[176:177]
	global_store_dwordx4 v[4:5], v[0:3], off
	s_barrier

; DI int tid_() { int t = threadIdx.x; asm volatile("" : "+v"(t)); return t; }
; DI void transpose_tile(const float* __restrict__ src, int Nsrc, int K, bf16_t* __restrict__ dst, int mode, int k0, int n0, float* tile  ) {
;     const int tid = tid_();
;     const int n4 = (tid & 15) * 4;
;     const int c = colmap(mode, n0 + n4);
; #pragma unroll
;     for (int i = 0; i < 2; ++i) {
;         const int kk = (tid >> 4) + 32 * i;
;         f32x4 v = {0.f, 0.f, 0.f, 0.f};
;         if (c >= 0) v = *(const f32x4*)(src + (size_t)(k0 + kk) * Nsrc + c);
;         tile[kk * 65 + n4] = v[0]; tile[kk * 65 + n4 + 1] = v[1]; tile[kk * 65 + n4 + 2] = v[2]; tile[kk * 65 + n4 + 3] = v[3];
;     }
;     __syncthreads();
; DI void prep_weights(const Params& P, unsigned char* smem, int L, int vb, int nvb, int part  ) {
;     ...
;         else if (idx < E2) { const int q = idx - E1; const int j = L * 2 + q / T_W2, t = q % T_W2; const int kt = t / 16, nt = t % 16;
;             transpose_tile(P.ffn_w_out + (size_t)j * DFF * D, D, DFF, (bf16_t*)(ws + OFF_W2 + j * SZ_W2), 0, kt * 64, nt * 64, tile); }
.LBB0_359:
	s_andn2_b64 vcc, exec, s[6:7]
	s_cbranch_vccnz .LBB0_361
	v_mov_b32_e32 v8, v223
	s_add_i32 s4, s8, 0xffffc900
	s_add_i32 s7, s9, 0xfffc9000
	s_and_b32 s6, s4, 0xfc0
	v_lshlrev_b32_e32 v0, 2, v8
	s_and_b32 s11, s7, 0x3c0
	v_and_b32_e32 v0, 60, v0
	v_ashrrev_i32_e32 v9, 4, v8
	v_or_b32_e32 v1, s11, v0
	v_readlane_b32 s12, v250, 42
	v_add_u32_e32 v6, s6, v9
	v_lshlrev_b32_e32 v176, 2, v1
	v_readlane_b32 s13, v250, 43
	v_ashrrev_i32_e32 v7, 31, v6
	v_lshlrev_b32_e32 v10, 2, v0
	v_lshl_add_u64 v[4:5], s[12:13], 0, v[176:177]
	v_lshlrev_b64 v[0:1], 12, v[6:7]
	v_lshl_add_u64 v[0:1], v[4:5], 0, v[0:1]
	global_load_dwordx4 v[0:3], v[0:1], off
	v_add_u32_e32 v20, 32, v6
	v_ashrrev_i32_e32 v21, 31, v20
	v_lshlrev_b64 v[20:21], 12, v[20:21]
	v_lshl_add_u64 v[20:21], v[4:5], 0, v[20:21]
	global_load_dwordx4 v[16:19], v[20:21], off
	s_movk_i32 s0, 0x104
	v_mul_lo_u32 v7, v9, s0
	v_add3_u32 v7, 0, v10, v7
	s_bfe_u32 s6, s7, 0x20008
	s_mul_i32 s6, s6, 44
	s_bfe_u32 s4, s4, 0x60006
	s_add_i32 s6, s6, s4
	s_lshl_b32 s4, s6, 8
	s_and_b32 s6, s7, 0xc0
	s_or_b32 s4, s4, s6
	v_readlane_b32 s6, v250, 40
	v_readlane_b32 s7, v250, 41
	s_waitcnt vmcnt(1)
	ds_write2_b32 v7, v0, v1 offset1:1
	ds_write2_b32 v7, v2, v3 offset0:2 offset1:3
	v_add_u32_e32 v4, 0x2080, v7
	s_waitcnt vmcnt(0)
	ds_write2_b32 v4, v16, v17 offset1:1
	v_add_u32_e32 v0, 0x2088, v7
	ds_write2_b32 v0, v18, v19 offset1:1
	v_lshlrev_b32_e32 v0, 3, v8
	v_ashrrev_i32_e32 v4, 3, v8
	v_and_b32_e32 v8, 56, v0
	v_mul_u32_u24_e32 v0, 0x104, v8
	v_lshlrev_b32_e32 v1, 2, v4
	v_add3_u32 v5, 0, v0, v1
	s_waitcnt lgkmcnt(0)
	s_barrier
	ds_read2_b32 v[0:1], v5 offset1:65
	ds_read2_b32 v[2:3], v5 offset0:130 offset1:195
	v_add_u32_e32 v5, 0x400, v5
	ds_read2_b32 v[6:7], v5 offset0:134 offset1:199
	v_lshlrev_b32_e32 v176, 1, v8
	v_and_b32_e32 v245, 64, v176
	v_and_b32_e32 v176, 48, v176
	v_lshl_or_b32 v176, v245, 8, v176
	s_waitcnt lgkmcnt(2)
	v_cvt_pk_bf16_f32 v0, v0, v1
	s_waitcnt lgkmcnt(1)
	v_cvt_pk_bf16_f32 v1, v2, v3
	ds_read2_b32 v[2:3], v5 offset0:4 offset1:69
	v_ashrrev_i32_e32 v5, 31, v4
	v_lshl_add_u64 v[4:5], v[4:5], 0, s[4:5]
	v_and_b32_e32 v246, 0xff, v4
	v_lshlrev_b32_e32 v246, 6, v246
	v_and_b32_e32 v4, 0xffffff00, v4
	v_lshlrev_b64 v[4:5], 7, v[4:5]
	v_or_b32_e32 v4, v4, v246
	v_lshl_add_u64 v[4:5], s[6:7], 0, v[4:5]
	s_waitcnt lgkmcnt(0)
	v_cvt_pk_bf16_f32 v2, v2, v3
	v_cvt_pk_bf16_f32 v3, v6, v7
	v_lshl_add_u64 v[4:5], v[4:5], 0, v[176:177]
	global_store_dwordx4 v[4:5], v[0:3], off
	s_barrier

; DI int tid_() { int t = threadIdx.x; asm volatile("" : "+v"(t)); return t; }
; DI void transpose_tile(const float* __restrict__ src, int Nsrc, int K, bf16_t* __restrict__ dst, int mode, int k0, int n0, float* tile  ) {
;     const int tid = tid_();
;     const int n4 = (tid & 15) * 4;
;     const int c = colmap(mode, n0 + n4);
; #pragma unroll
;     for (int i = 0; i < 2; ++i) {
;         const int kk = (tid >> 4) + 32 * i;
;         f32x4 v = {0.f, 0.f, 0.f, 0.f};
;         if (c >= 0) v = *(const f32x4*)(src + (size_t)(k0 + kk) * Nsrc + c);
;         tile[kk * 65 + n4] = v[0]; tile[kk * 65 + n4 + 1] = v[1]; tile[kk * 65 + n4 + 2] = v[2]; tile[kk * 65 + n4 + 3] = v[3];
;     }
;     __syncthreads();
; DI void prep_weights(const Params& P, unsigned char* smem, int L, int vb, int nvb, int part  ) {
;     ...
;         else if (idx < E5) { const int t = idx - E4; const int kt = t / 16, nt = t % 16;
;             transpose_tile(P.ple_w_gate + (size_t)L * D * D, D, D, (bf16_t*)(ws + OFF_WG + L * SZ_WSQ), 0, kt * 64, nt * 64, tile); }
;         else { const int t = idx - E5; const int kt = t / 16, nt = t % 16;
;             transpose_tile(P.ple_w_proj + (size_t)L * PLE * D, D, PLE, (bf16_t*)(ws + OFF_WP + L * SZ_WP), 0, kt * 64, nt * 64, tile); }
.LBB0_471:
	s_cmpk_gt_i32 s10, 0xaff
	s_mov_b64 s[6:7], -1
	s_cbranch_scc0 .LBB0_499
	s_cmpk_gt_u32 s10, 0x107f
	s_cbranch_scc0 .LBB0_496
	s_cmpk_gt_u32 s10, 0x143f
	s_cbranch_scc0 .LBB0_483
	s_cmpk_gt_u32 s10, 0x153f
	s_cbranch_scc0 .LBB0_480
	s_and_b32 s11, s9, 0x3c0
	s_cmpk_gt_u32 s10, 0x163f
	s_cbranch_scc0 .LBB0_477
	v_mov_b32_e32 v8, v223
	s_and_b32 s4, s8, 0x7fffffc0
	s_addk_i32 s4, 0xa700
	v_lshlrev_b32_e32 v0, 2, v8
	v_and_b32_e32 v0, 60, v0
	v_ashrrev_i32_e32 v9, 4, v8
	v_or_b32_e32 v1, s11, v0
	v_readlane_b32 s0, v250, 54
	v_add_u32_e32 v6, s4, v9
	v_lshlrev_b32_e32 v176, 2, v1
	v_readlane_b32 s1, v250, 55
	v_ashrrev_i32_e32 v7, 31, v6
	v_lshlrev_b32_e32 v10, 2, v0
	v_lshl_add_u64 v[4:5], s[0:1], 0, v[176:177]
	v_lshlrev_b64 v[0:1], 12, v[6:7]
	v_lshl_add_u64 v[0:1], v[4:5], 0, v[0:1]
	global_load_dwordx4 v[0:3], v[0:1], off
	v_add_u32_e32 v20, 32, v6
	v_ashrrev_i32_e32 v21, 31, v20
	v_lshlrev_b64 v[20:21], 12, v[20:21]
	v_lshl_add_u64 v[20:21], v[4:5], 0, v[20:21]
	global_load_dwordx4 v[16:19], v[20:21], off
	s_movk_i32 s0, 0x104
	v_mul_lo_u32 v7, v9, s0
	v_add3_u32 v7, 0, v10, v7
	s_and_b32 s6, s10, 12
	s_lshr_b32 s4, s4, 6
	s_add_i32 s4, s4, s6
	s_lshl_b64 s[6:7], s[4:5], 8
	s_and_b32 s4, s9, 0xc0
	s_or_b32 s6, s6, s4
	s_waitcnt vmcnt(1)
	ds_write2_b32 v7, v0, v1 offset1:1
	ds_write2_b32 v7, v2, v3 offset0:2 offset1:3
	v_add_u32_e32 v4, 0x2080, v7
	s_waitcnt vmcnt(0)
	ds_write2_b32 v4, v16, v17 offset1:1
	v_add_u32_e32 v0, 0x2088, v7
	ds_write2_b32 v0, v18, v19 offset1:1
	v_lshlrev_b32_e32 v0, 3, v8
	v_ashrrev_i32_e32 v4, 3, v8
	v_and_b32_e32 v8, 56, v0
	v_mul_u32_u24_e32 v0, 0x104, v8
	v_lshlrev_b32_e32 v1, 2, v4
	v_add3_u32 v5, 0, v0, v1
	s_waitcnt lgkmcnt(0)
	s_barrier
	ds_read2_b32 v[0:1], v5 offset1:65
	ds_read2_b32 v[2:3], v5 offset0:130 offset1:195
	v_add_u32_e32 v5, 0x400, v5
	ds_read2_b32 v[6:7], v5 offset0:134 offset1:199
	v_lshlrev_b32_e32 v176, 1, v8
	v_and_b32_e32 v245, 64, v176
	v_and_b32_e32 v176, 48, v176
	v_lshl_or_b32 v176, v245, 8, v176
	s_waitcnt lgkmcnt(2)
	v_cvt_pk_bf16_f32 v0, v0, v1
	s_waitcnt lgkmcnt(1)
	v_cvt_pk_bf16_f32 v1, v2, v3
	ds_read2_b32 v[2:3], v5 offset0:4 offset1:69
	v_ashrrev_i32_e32 v5, 31, v4
	v_lshl_add_u64 v[4:5], s[6:7], 0, v[4:5]
	v_readlane_b32 s6, v250, 46
	v_and_b32_e32 v246, 0xff, v4
	v_lshlrev_b32_e32 v246, 6, v246
	v_and_b32_e32 v4, 0xffffff00, v4
	v_lshlrev_b64 v[4:5], 7, v[4:5]
	v_or_b32_e32 v4, v4, v246
	v_readlane_b32 s7, v250, 47
	s_waitcnt lgkmcnt(0)
	v_cvt_pk_bf16_f32 v2, v2, v3
	v_cvt_pk_bf16_f32 v3, v6, v7
	v_lshl_add_u64 v[4:5], s[6:7], 0, v[4:5]
	v_lshl_add_u64 v[4:5], v[4:5], 0, v[176:177]
	global_store_dwordx4 v[4:5], v[0:3], off
	s_barrier
	s_mov_b64 s[6:7], 0
.LBB0_477:
	s_andn2_b64 vcc, exec, s[6:7]
	s_cbranch_vccnz .LBB0_479
	v_mov_b32_e32 v8, v223
	s_and_b32 s4, s8, 0x7fc0
	s_addk_i32 s4, 0xab00
	v_lshlrev_b32_e32 v0, 2, v8
	v_and_b32_e32 v0, 60, v0
	v_ashrrev_i32_e32 v9, 4, v8
	v_or_b32_e32 v1, s11, v0
	v_readlane_b32 s0, v250, 56
	v_add_u32_e32 v6, s4, v9
	v_lshlrev_b32_e32 v176, 2, v1
	v_readlane_b32 s1, v250, 57
	v_ashrrev_i32_e32 v7, 31, v6
	v_lshlrev_b32_e32 v10, 2, v0
	v_lshl_add_u64 v[4:5], s[0:1], 0, v[176:177]
	v_lshlrev_b64 v[0:1], 12, v[6:7]
	v_lshl_add_u64 v[0:1], v[4:5], 0, v[0:1]
	global_load_dwordx4 v[0:3], v[0:1], off
	v_add_u32_e32 v20, 32, v6
	v_ashrrev_i32_e32 v21, 31, v20
	v_lshlrev_b64 v[20:21], 12, v[20:21]
	v_lshl_add_u64 v[20:21], v[4:5], 0, v[20:21]
	global_load_dwordx4 v[16:19], v[20:21], off
	s_movk_i32 s0, 0x104
	v_mul_lo_u32 v7, v9, s0
	v_add3_u32 v7, 0, v10, v7
	s_and_b32 s6, s8, 48
	s_lshr_b32 s4, s4, 6
	s_add_i32 s4, s4, s6
	s_lshl_b64 s[6:7], s[4:5], 8
	s_and_b32 s4, s9, 0xc0
	s_or_b32 s6, s6, s4
	s_waitcnt vmcnt(1)
	ds_write2_b32 v7, v0, v1 offset1:1
	ds_write2_b32 v7, v2, v3 offset0:2 offset1:3
	v_add_u32_e32 v4, 0x2080, v7
	s_waitcnt vmcnt(0)
	ds_write2_b32 v4, v16, v17 offset1:1
	v_add_u32_e32 v0, 0x2088, v7
	ds_write2_b32 v0, v18, v19 offset1:1
	v_lshlrev_b32_e32 v0, 3, v8
	v_ashrrev_i32_e32 v4, 3, v8
	v_and_b32_e32 v8, 56, v0
	v_mul_u32_u24_e32 v0, 0x104, v8
	v_lshlrev_b32_e32 v1, 2, v4
	v_add3_u32 v5, 0, v0, v1
	s_waitcnt lgkmcnt(0)
	s_barrier
	ds_read2_b32 v[0:1], v5 offset1:65
	ds_read2_b32 v[2:3], v5 offset0:130 offset1:195
	v_add_u32_e32 v5, 0x400, v5
	ds_read2_b32 v[6:7], v5 offset0:134 offset1:199
	v_lshlrev_b32_e32 v176, 1, v8
	v_and_b32_e32 v245, 64, v176
	v_and_b32_e32 v176, 48, v176
	v_lshl_or_b32 v176, v245, 8, v176
	s_waitcnt lgkmcnt(2)
	v_cvt_pk_bf16_f32 v0, v0, v1
	s_waitcnt lgkmcnt(1)
	v_cvt_pk_bf16_f32 v1, v2, v3
	ds_read2_b32 v[2:3], v5 offset0:4 offset1:69
	v_ashrrev_i32_e32 v5, 31, v4
	v_lshl_add_u64 v[4:5], s[6:7], 0, v[4:5]
	v_readlane_b32 s6, v250, 48
	v_and_b32_e32 v246, 0xff, v4
	v_lshlrev_b32_e32 v246, 6, v246
	v_and_b32_e32 v4, 0xffffff00, v4
	v_lshlrev_b64 v[4:5], 7, v[4:5]
	v_or_b32_e32 v4, v4, v246
	v_readlane_b32 s7, v250, 49
	s_waitcnt lgkmcnt(0)
	v_cvt_pk_bf16_f32 v2, v2, v3
	v_cvt_pk_bf16_f32 v3, v6, v7
	v_lshl_add_u64 v[4:5], s[6:7], 0, v[4:5]
	v_lshl_add_u64 v[4:5], v[4:5], 0, v[176:177]
	global_store_dwordx4 v[4:5], v[0:3], off
	s_barrier

; DI int tid_() { int t = threadIdx.x; asm volatile("" : "+v"(t)); return t; }
; DI void transpose_tile(const float* __restrict__ src, int Nsrc, int K, bf16_t* __restrict__ dst, int mode, int k0, int n0, float* tile  ) {
;     const int tid = tid_();
;     const int n4 = (tid & 15) * 4;
;     const int c = colmap(mode, n0 + n4);
; #pragma unroll
;     for (int i = 0; i < 2; ++i) {
;         const int kk = (tid >> 4) + 32 * i;
;         f32x4 v = {0.f, 0.f, 0.f, 0.f};
;         if (c >= 0) v = *(const f32x4*)(src + (size_t)(k0 + kk) * Nsrc + c);
;         tile[kk * 65 + n4] = v[0]; tile[kk * 65 + n4 + 1] = v[1]; tile[kk * 65 + n4 + 2] = v[2]; tile[kk * 65 + n4 + 3] = v[3];
;     }
;     __syncthreads();
; DI void prep_weights(const Params& P, unsigned char* smem, int L, int vb, int nvb, int part  ) {
;     ...
;         else if (idx < E4) { const int t = idx - E3; const int kt = t / 16, nt = t % 16;
;             transpose_tile(P.mix_w_out + (size_t)L * D * D, D, D, (bf16_t*)(ws + OFF_WOUT + L * SZ_WSQ), 0, kt * 64, nt * 64, tile); }
.LBB0_480:
	s_andn2_b64 vcc, exec, s[6:7]
	s_cbranch_vccnz .LBB0_482
	v_mov_b32_e32 v8, v223
	s_and_b32 s4, s8, 0x7fc0
	s_addk_i32 s4, 0xaf00
	v_lshlrev_b32_e32 v0, 2, v8
	s_and_b32 s6, s9, 0x3c0
	v_and_b32_e32 v0, 60, v0
	v_ashrrev_i32_e32 v9, 4, v8
	v_or_b32_e32 v1, s6, v0
	v_readlane_b32 s0, v249, 10
	v_add_u32_e32 v6, s4, v9
	v_lshlrev_b32_e32 v176, 2, v1
	v_readlane_b32 s1, v249, 11
	v_ashrrev_i32_e32 v7, 31, v6
	v_lshlrev_b32_e32 v10, 2, v0
	v_lshl_add_u64 v[4:5], s[0:1], 0, v[176:177]
	v_lshlrev_b64 v[0:1], 12, v[6:7]
	v_lshl_add_u64 v[0:1], v[4:5], 0, v[0:1]
	global_load_dwordx4 v[0:3], v[0:1], off
	v_add_u32_e32 v20, 32, v6
	v_ashrrev_i32_e32 v21, 31, v20
	v_lshlrev_b64 v[20:21], 12, v[20:21]
	v_lshl_add_u64 v[20:21], v[4:5], 0, v[20:21]
	global_load_dwordx4 v[16:19], v[20:21], off
	s_movk_i32 s0, 0x104
	v_mul_lo_u32 v7, v9, s0
	v_add3_u32 v7, 0, v10, v7
	s_and_b32 s6, s8, 48
	s_lshr_b32 s4, s4, 6
	s_add_i32 s4, s4, s6
	s_lshl_b64 s[6:7], s[4:5], 8
	s_and_b32 s4, s9, 0xc0
	s_or_b32 s6, s6, s4
	s_waitcnt vmcnt(1)
	ds_write2_b32 v7, v0, v1 offset1:1
	ds_write2_b32 v7, v2, v3 offset0:2 offset1:3
	v_add_u32_e32 v4, 0x2080, v7
	s_waitcnt vmcnt(0)
	ds_write2_b32 v4, v16, v17 offset1:1
	v_add_u32_e32 v0, 0x2088, v7
	ds_write2_b32 v0, v18, v19 offset1:1
	v_lshlrev_b32_e32 v0, 3, v8
	v_ashrrev_i32_e32 v4, 3, v8
	v_and_b32_e32 v8, 56, v0
	v_mul_u32_u24_e32 v0, 0x104, v8
	v_lshlrev_b32_e32 v1, 2, v4
	v_add3_u32 v5, 0, v0, v1
	s_waitcnt lgkmcnt(0)
	s_barrier
	ds_read2_b32 v[0:1], v5 offset1:65
	ds_read2_b32 v[2:3], v5 offset0:130 offset1:195
	v_add_u32_e32 v5, 0x400, v5
	ds_read2_b32 v[6:7], v5 offset0:134 offset1:199
	v_lshlrev_b32_e32 v176, 1, v8
	v_and_b32_e32 v245, 64, v176
	v_and_b32_e32 v176, 48, v176
	v_lshl_or_b32 v176, v245, 8, v176
	s_waitcnt lgkmcnt(2)
	v_cvt_pk_bf16_f32 v0, v0, v1
	s_waitcnt lgkmcnt(1)
	v_cvt_pk_bf16_f32 v1, v2, v3
	ds_read2_b32 v[2:3], v5 offset0:4 offset1:69
	v_ashrrev_i32_e32 v5, 31, v4
	v_lshl_add_u64 v[4:5], s[6:7], 0, v[4:5]
	v_readlane_b32 s6, v250, 50
	v_and_b32_e32 v246, 0xff, v4
	v_lshlrev_b32_e32 v246, 6, v246
	v_and_b32_e32 v4, 0xffffff00, v4
	v_lshlrev_b64 v[4:5], 7, v[4:5]
	v_or_b32_e32 v4, v4, v246
	v_readlane_b32 s7, v250, 51
	s_waitcnt lgkmcnt(0)
	v_cvt_pk_bf16_f32 v2, v2, v3
	v_cvt_pk_bf16_f32 v3, v6, v7
	v_lshl_add_u64 v[4:5], s[6:7], 0, v[4:5]
	v_lshl_add_u64 v[4:5], v[4:5], 0, v[176:177]
	global_store_dwordx4 v[4:5], v[0:3], off
	s_barrier

; DI int tid_() { int t = threadIdx.x; asm volatile("" : "+v"(t)); return t; }
; DI void transpose_tile(const float* __restrict__ src, int Nsrc, int K, bf16_t* __restrict__ dst, int mode, int k0, int n0, float* tile  ) {
;     const int tid = tid_();
;     const int n4 = (tid & 15) * 4;
;     const int c = colmap(mode, n0 + n4);
; #pragma unroll
;     for (int i = 0; i < 2; ++i) {
;         const int kk = (tid >> 4) + 32 * i;
;         f32x4 v = {0.f, 0.f, 0.f, 0.f};
;         if (c >= 0) v = *(const f32x4*)(src + (size_t)(k0 + kk) * Nsrc + c);
;         tile[kk * 65 + n4] = v[0]; tile[kk * 65 + n4 + 1] = v[1]; tile[kk * 65 + n4 + 2] = v[2]; tile[kk * 65 + n4 + 3] = v[3];
;     }
;     __syncthreads();
; DI void prep_weights(const Params& P, unsigned char* smem, int L, int vb, int nvb, int part  ) {
;     ...
;         else if (idx < E2) { const int q = idx - E1; const int j = L * 2 + q / T_W2, t = q % T_W2; const int kt = t / 16, nt = t % 16;
;             transpose_tile(P.ffn_w_out + (size_t)j * DFF * D, D, DFF, (bf16_t*)(ws + OFF_W2 + j * SZ_W2), 0, kt * 64, nt * 64, tile); }
.LBB0_496:
	s_andn2_b64 vcc, exec, s[6:7]
	s_cbranch_vccnz .LBB0_498
	s_add_i32 s4, s10, 0xfffff500
	s_cmpk_gt_u32 s4, 0x2bf
	s_cselect_b64 s[6:7], -1, 0
	v_cndmask_b32_e64 v0, 0, 1, s[6:7]
	s_add_i32 s7, s10, 0xfffff240
	v_readfirstlane_b32 s6, v0
	s_or_b32 s6, s6, 2
	s_cmpk_lt_u32 s4, 0x2c0
	v_readlane_b32 s12, v249, 53
	s_cselect_b32 s4, s4, s7
	s_mul_i32 s7, s6, 0xb00000
	v_readlane_b32 s22, v249, 63
	v_readlane_b32 s13, v249, 54
	v_readlane_b32 s23, v248, 0
	s_add_u32 s12, s22, s7
	s_addc_u32 s13, s23, 0
	s_mul_i32 s6, s6, 0x580000
	v_readlane_b32 s7, v250, 20
	v_readlane_b32 s14, v249, 55
	s_add_u32 s6, s7, s6
	v_readlane_b32 s7, v250, 21
	v_mov_b32_e32 v8, v223
	v_readlane_b32 s15, v249, 56
	s_addc_u32 s7, s7, 0
	s_lshl_b32 s11, s4, 2
	s_lshl_b32 s14, s4, 6
	s_and_b32 s11, s11, 0xfc0
	v_lshlrev_b32_e32 v0, 2, v8
	s_and_b32 s15, s14, 0x3c0
	v_and_b32_e32 v0, 60, v0
	v_ashrrev_i32_e32 v9, 4, v8
	v_or_b32_e32 v1, s15, v0
	v_add_u32_e32 v6, s11, v9
	v_lshlrev_b32_e32 v176, 2, v1
	v_ashrrev_i32_e32 v7, 31, v6
	v_lshlrev_b32_e32 v10, 2, v0
	v_lshl_add_u64 v[4:5], s[12:13], 0, v[176:177]
	v_lshlrev_b64 v[0:1], 12, v[6:7]
	v_lshl_add_u64 v[0:1], v[4:5], 0, v[0:1]
	global_load_dwordx4 v[0:3], v[0:1], off
	v_add_u32_e32 v20, 32, v6
	v_ashrrev_i32_e32 v21, 31, v20
	v_lshlrev_b64 v[20:21], 12, v[20:21]
	v_lshl_add_u64 v[20:21], v[4:5], 0, v[20:21]
	global_load_dwordx4 v[16:19], v[20:21], off
	s_movk_i32 s0, 0x104
	v_mul_lo_u32 v7, v9, s0
	v_add3_u32 v7, 0, v10, v7
	s_bfe_u32 s11, s14, 0x20008
	s_mul_i32 s11, s11, 44
	s_bfe_u32 s4, s4, 0x60004
	s_add_i32 s11, s11, s4
	s_lshl_b32 s4, s11, 8
	s_and_b32 s11, s14, 0xc0
	s_or_b32 s4, s4, s11
	v_readlane_b32 s16, v249, 57
	v_readlane_b32 s17, v249, 58
	v_readlane_b32 s18, v249, 59
	v_readlane_b32 s19, v249, 60
	v_readlane_b32 s20, v249, 61
	v_readlane_b32 s21, v249, 62
	v_readlane_b32 s24, v248, 1
	v_readlane_b32 s25, v248, 2
	v_readlane_b32 s26, v248, 3
	v_readlane_b32 s27, v248, 4
	s_waitcnt vmcnt(1)
	ds_write2_b32 v7, v0, v1 offset1:1
	ds_write2_b32 v7, v2, v3 offset0:2 offset1:3
	v_add_u32_e32 v4, 0x2080, v7
	s_waitcnt vmcnt(0)
	ds_write2_b32 v4, v16, v17 offset1:1
	v_add_u32_e32 v0, 0x2088, v7
	ds_write2_b32 v0, v18, v19 offset1:1
	v_lshlrev_b32_e32 v0, 3, v8
	v_ashrrev_i32_e32 v4, 3, v8
	v_and_b32_e32 v8, 56, v0
	v_mul_u32_u24_e32 v0, 0x104, v8
	v_lshlrev_b32_e32 v1, 2, v4
	v_add3_u32 v5, 0, v0, v1
	s_waitcnt lgkmcnt(0)
	s_barrier
	ds_read2_b32 v[0:1], v5 offset1:65
	ds_read2_b32 v[2:3], v5 offset0:130 offset1:195
	v_add_u32_e32 v5, 0x400, v5
	ds_read2_b32 v[6:7], v5 offset0:134 offset1:199
	v_lshlrev_b32_e32 v176, 1, v8
	v_and_b32_e32 v245, 64, v176
	v_and_b32_e32 v176, 48, v176
	v_lshl_or_b32 v176, v245, 8, v176
	s_waitcnt lgkmcnt(2)
	v_cvt_pk_bf16_f32 v0, v0, v1
	s_waitcnt lgkmcnt(1)
	v_cvt_pk_bf16_f32 v1, v2, v3
	ds_read2_b32 v[2:3], v5 offset0:4 offset1:69
	v_ashrrev_i32_e32 v5, 31, v4
	v_lshl_add_u64 v[4:5], v[4:5], 0, s[4:5]
	v_and_b32_e32 v246, 0xff, v4
	v_lshlrev_b32_e32 v246, 6, v246
	v_and_b32_e32 v4, 0xffffff00, v4
	v_lshlrev_b64 v[4:5], 7, v[4:5]
	v_or_b32_e32 v4, v4, v246
	v_lshl_add_u64 v[4:5], s[6:7], 0, v[4:5]
	s_waitcnt lgkmcnt(0)
	v_cvt_pk_bf16_f32 v2, v2, v3
	v_cvt_pk_bf16_f32 v3, v6, v7
	v_lshl_add_u64 v[4:5], v[4:5], 0, v[176:177]
	global_store_dwordx4 v[4:5], v[0:3], off
	s_barrier
